# light group barriers: L1 invalidate issued right after the arrive atomic (overlaps its round trip and the flag wait) instead of after the flag
# speedup vs baseline: 1.0173x; 1.0072x over previous
.LBB0_295:
	s_or_b64 exec, exec, s[10:11]
	buffer_inv sc1
	s_waitcnt vmcnt(0)
	v_readfirstlane_b32 s3, v1
	s_add_u32 s6, s6, 0x34100
	s_addc_u32 s7, s7, 0
	v_add_u32_e32 v0, s3, v0
	v_cmp_ne_u32_e32 vcc, 31, v0
	s_and_saveexec_b64 s[8:9], vcc
	s_xor_b64 s[8:9], exec, s[8:9]
	s_cbranch_execz .LBB0_297
	v_mov_b32_e32 v0, 0
	global_load_dword v1, v0, s[6:7] sc1
	s_waitcnt vmcnt(0)
	v_cmp_ne_u32_e32 vcc, 0, v1
	s_cbranch_vccz .LBB0_611

.LBB0_299:
	s_or_b64 exec, exec, s[8:9]
	s_waitcnt vmcnt(0)
	s_waitcnt vmcnt(0)

.LBB0_633:
	s_or_b64 exec, exec, s[10:11]
	buffer_inv sc1
	s_waitcnt vmcnt(0)
	v_readfirstlane_b32 s3, v1
	s_add_u32 s6, s6, 0x33100
	s_addc_u32 s7, s7, 0
	v_add_u32_e32 v0, s3, v0
	v_cmp_ne_u32_e32 vcc, 31, v0
	s_and_saveexec_b64 s[8:9], vcc
	s_xor_b64 s[8:9], exec, s[8:9]
	s_cbranch_execz .LBB0_635
	v_mov_b32_e32 v0, 0
	global_load_dword v1, v0, s[6:7] sc1
	s_waitcnt vmcnt(0)
	v_cmp_ne_u32_e32 vcc, 0, v1
	s_cbranch_vccz .LBB0_778

.LBB0_800:
	s_or_b64 exec, exec, s[10:11]
	buffer_inv sc1
	s_waitcnt vmcnt(0)
	v_readfirstlane_b32 s3, v1
	s_add_u32 s6, s6, 0x35100
	s_addc_u32 s7, s7, 0
	v_add_u32_e32 v0, s3, v0
	v_cmp_ne_u32_e32 vcc, 31, v0
	s_and_saveexec_b64 s[8:9], vcc
	s_xor_b64 s[8:9], exec, s[8:9]
	s_cbranch_execz .LBB0_802
	v_mov_b32_e32 v0, 0
	global_load_dword v1, v0, s[6:7] sc1
	s_waitcnt vmcnt(0)
	v_cmp_ne_u32_e32 vcc, 0, v1
	s_cbranch_vccz .LBB0_889

.LBB0_911:
	s_or_b64 exec, exec, s[10:11]
	buffer_inv sc1
	s_waitcnt vmcnt(0)
	v_readfirstlane_b32 s3, v1
	s_nop 1
	v_add_u32_e32 v0, s3, v0
	v_cmp_ne_u32_e32 vcc, 31, v0
	s_and_saveexec_b64 s[8:9], vcc
	s_xor_b64 s[8:9], exec, s[8:9]
	s_cbranch_execz .LBB0_913
	v_mov_b32_e32 v0, 0
	global_load_dword v1, v0, s[6:7] offset:256 sc1
	s_waitcnt vmcnt(0)
	v_cmp_ne_u32_e32 vcc, 0, v1
	s_cbranch_vccz .LBB0_1397

.LBB0_1419:
	s_or_b64 exec, exec, s[10:11]
	buffer_inv sc1
	s_waitcnt vmcnt(0)
	v_readfirstlane_b32 s3, v1
	s_add_u32 s6, s6, 0x31100
	s_addc_u32 s7, s7, 0
	v_add_u32_e32 v0, s3, v0
	v_cmp_ne_u32_e32 vcc, 31, v0
	s_and_saveexec_b64 s[8:9], vcc
	s_xor_b64 s[8:9], exec, s[8:9]
	s_cbranch_execz .LBB0_1421
	v_mov_b32_e32 v0, 0
	global_load_dword v1, v0, s[6:7] sc1
	s_waitcnt vmcnt(0)
	v_cmp_ne_u32_e32 vcc, 0, v1
	s_cbranch_vccz .LBB0_1480

.LBB0_1502:
	s_or_b64 exec, exec, s[10:11]
	buffer_inv sc1
	s_waitcnt vmcnt(0)
	v_readfirstlane_b32 s3, v1
	s_add_u32 s6, s6, 0x32100
	s_addc_u32 s7, s7, 0
	v_add_u32_e32 v0, s3, v0
	v_cmp_ne_u32_e32 vcc, 31, v0
	s_and_saveexec_b64 s[8:9], vcc
	s_xor_b64 s[8:9], exec, s[8:9]
	s_cbranch_execz .LBB0_1504
	v_mov_b32_e32 v0, 0
	global_load_dword v1, v0, s[6:7] sc1
	s_waitcnt vmcnt(0)
	v_cmp_ne_u32_e32 vcc, 0, v1
	s_cbranch_vccz .LBB0_1527
